# rope / qk-norm phase software-pipelined across rows: next row's loads issued ahead of the current row's last stores, one counted wait at the row top
# speedup vs baseline: 1.0006x; 1.0006x over previous
.Lgb3_done:
.LBB0_989:
	s_or_b64 exec, exec, s[2:3]
	v_mov_b32_e32 v0, v214
	v_readlane_b32 s3, v253, 0
	s_waitcnt lgkmcnt(0)
	s_barrier
	s_lshl_b32 s3, s3, 3
	v_readfirstlane_b32 s2, v0
	s_ashr_i32 s2, s2, 6
	s_add_i32 s2, s3, s2
	s_cmpk_gt_i32 s2, 0x23ff
	s_cbranch_scc1 .LBB0_1012
	v_and_b32_e32 v58, 63, v0
	v_lshlrev_b32_e32 v3, 3, v0
	v_bfe_u32 v1, v0, 2, 1
	v_and_b32_e32 v6, 24, v3
	v_mov_b32_e32 v3, s71
	v_mov_b32_e32 v5, s69
	v_cmp_gt_u32_e32 vcc, 48, v58
	v_lshlrev_b32_e32 v4, 6, v1
	v_lshlrev_b32_e32 v176, 8, v1
	v_cndmask_b32_e32 v9, v3, v5, vcc
	v_mov_b32_e32 v3, s70
	v_mov_b32_e32 v5, s68
	v_cmp_eq_u32_e64 s[6:7], 0, v1
	v_xor_b32_e32 v1, 1, v218
	v_cndmask_b32_e32 v8, v3, v5, vcc
	v_cmp_lt_i32_e32 vcc, v1, v219
	v_or_b32_e32 v3, 1, v6
	v_or_b32_e32 v5, 2, v6
	v_cndmask_b32_e32 v1, v218, v1, vcc
	v_lshlrev_b32_e32 v59, 2, v1
	v_xor_b32_e32 v1, 2, v218
	v_cmp_lt_i32_e32 vcc, v1, v219
	v_or_b32_e32 v7, 3, v6
	v_cvt_f32_ubyte0_e32 v3, v3
	v_cndmask_b32_e32 v1, v218, v1, vcc
	v_lshlrev_b32_e32 v60, 2, v1
	v_xor_b32_e32 v1, 4, v218
	v_cmp_lt_i32_e32 vcc, v1, v219
	v_cvt_f32_ubyte0_e32 v5, v5
	v_cvt_f32_ubyte0_e32 v7, v7
	v_cndmask_b32_e32 v1, v218, v1, vcc
	v_lshlrev_b32_e32 v61, 2, v1
	v_cvt_f32_ubyte0_e32 v1, v6
	v_mul_f32_e32 v1, 0xbed49a78, v1
	v_exp_f32_e32 v1, v1
	v_mul_f32_e32 v3, 0xbed49a78, v3
	v_mul_f32_e32 v5, 0xbed49a78, v5
	v_mul_f32_e32 v7, 0xbed49a78, v7
	v_exp_f32_e32 v3, v3
	v_exp_f32_e32 v5, v5
	v_exp_f32_e32 v7, v7
	v_mul_f32_e32 v62, 0.15915494, v1
	v_or_b32_e32 v1, 4, v6
	v_cvt_f32_ubyte0_e32 v1, v1
	v_mul_f32_e32 v1, 0xbed49a78, v1
	v_mul_f32_e32 v63, 0.15915494, v3
	v_mul_f32_e32 v64, 0.15915494, v5
	v_mul_f32_e32 v65, 0.15915494, v7
	v_exp_f32_e32 v1, v1
	v_or_b32_e32 v3, 5, v6
	v_or_b32_e32 v5, 6, v6
	v_or_b32_e32 v7, 7, v6
	v_cvt_f32_ubyte0_e32 v3, v3
	v_cvt_f32_ubyte0_e32 v5, v5
	v_cvt_f32_ubyte0_e32 v7, v7
	v_mul_f32_e32 v3, 0xbed49a78, v3
	v_mul_f32_e32 v5, 0xbed49a78, v5
	v_mul_f32_e32 v7, 0xbed49a78, v7
	s_lshl_b32 s90, s96, 7
	v_exp_f32_e32 v3, v3
	v_exp_f32_e32 v5, v5
	v_exp_f32_e32 v7, v7
	v_lshlrev_b32_e32 v2, 4, v0
	v_lshl_add_u64 v[8:9], s[90:91], 2, v[8:9]
	v_mul_f32_e32 v66, 0.15915494, v1
	v_lshlrev_b32_e32 v1, 5, v0
	v_and_b32_e32 v0, 1, v0
	v_lshl_add_u64 v[8:9], v[8:9], 0, v[176:177]
	v_lshlrev_b32_e32 v176, 2, v6
	v_lshlrev_b32_e32 v0, 4, v0
	s_movk_i32 s3, 0x7c0
	v_readlane_b32 s4, v253, 56
	v_and_b32_e32 v2, 0x380, v2
	v_lshl_add_u64 v[8:9], v[8:9], 0, v[176:177]
	v_and_or_b32 v176, v1, s3, v0
	v_readlane_b32 s5, v253, 57
	v_mul_f32_e32 v67, 0.15915494, v3
	v_mul_f32_e32 v68, 0.15915494, v5
	v_mul_f32_e32 v69, 0.15915494, v7
	v_lshlrev_b32_e32 v70, 3, v58
	v_lshl_add_u64 v[10:11], s[4:5], 0, v[176:177]
	v_lshlrev_b32_e32 v176, 1, v2
	v_lshlrev_b32_e32 v12, 1, v4
	v_lshlrev_b32_e32 v14, 1, v6
	s_ashr_i32 s15, s2, 31
	s_mov_b32 s14, s2
	s_lshl_b64 s[14:15], s[14:15], 13
	v_readlane_b32 s20, v253, 56
	v_readlane_b32 s21, v253, 57
	s_add_u32 s20, s20, s14
	s_addc_u32 s21, s21, s15
	v_lshl_add_u64 v[116:117], s[20:21], 0, v[176:177]
	v_mov_b32_e32 v119, v177
	v_mov_b32_e32 v118, v12
	v_lshl_add_u64 v[116:117], v[116:117], 0, v[118:119]
	v_mov_b32_e32 v118, v14
	v_lshl_add_u64 v[116:117], v[116:117], 0, v[118:119]
	s_mov_b64 s[22:23], 0x1600
	v_lshl_add_u64 v[120:121], v[116:117], 0, s[22:23]
	s_mov_b64 s[22:23], 0x1000
	v_lshl_add_u64 v[116:117], v[116:117], 0, s[22:23]
	global_load_dwordx4 v[100:103], v[116:117], off offset:1536
	global_load_dwordx4 v[104:107], v[120:121], off offset:64
	global_load_dword v124, v[8:9], off
	v_lshl_add_u64 v[122:123], v[10:11], 0, s[14:15]
	global_load_dwordx4 v[126:129], v[122:123], off
	global_load_dwordx4 v[130:133], v[122:123], off offset:32
	global_load_dwordx4 v[108:111], v[122:123], off offset:2048
	global_load_dwordx4 v[112:115], v[122:123], off offset:2080
	s_waitcnt vmcnt(0)
	s_branch .LBB0_992
.LBB0_991:
	s_waitcnt lgkmcnt(0)
	s_add_i32 s14, s2, s88
	s_cmpk_gt_i32 s14, 0x23ff
	s_cselect_b32 s14, s2, s14
	s_ashr_i32 s15, s14, 31
	s_lshl_b64 s[14:15], s[14:15], 13
	v_readlane_b32 s20, v253, 56
	v_readlane_b32 s21, v253, 57
	s_add_u32 s20, s20, s14
	s_addc_u32 s21, s21, s15
	v_lshl_add_u64 v[116:117], s[20:21], 0, v[176:177]
	v_mov_b32_e32 v119, v177
	v_mov_b32_e32 v118, v12
	v_lshl_add_u64 v[116:117], v[116:117], 0, v[118:119]
	v_mov_b32_e32 v118, v14
	v_lshl_add_u64 v[116:117], v[116:117], 0, v[118:119]
	s_mov_b64 s[22:23], 0x1600
	v_lshl_add_u64 v[120:121], v[116:117], 0, s[22:23]
	s_mov_b64 s[22:23], 0x1000
	v_lshl_add_u64 v[116:117], v[116:117], 0, s[22:23]
	global_load_dwordx4 v[100:103], v[116:117], off offset:1536
	global_load_dwordx4 v[104:107], v[120:121], off offset:64
	global_load_dword v124, v[8:9], off
	v_lshl_add_u64 v[122:123], v[10:11], 0, s[14:15]
	global_load_dwordx4 v[126:129], v[122:123], off
	global_load_dwordx4 v[130:133], v[122:123], off offset:32
	global_load_dwordx4 v[108:111], v[122:123], off offset:2048
	global_load_dwordx4 v[112:115], v[122:123], off offset:2080
	v_add_f32_e32 v13, v15, v71
	v_fmamk_f32 v13, v13, 0x3c000000, v215
	v_mul_f32_e32 v15, 0x4f800000, v13
	v_cmp_gt_f32_e32 vcc, s92, v13
	s_add_i32 s2, s2, s88
	s_cmpk_gt_i32 s2, 0x23ff
	v_cndmask_b32_e32 v13, v13, v15, vcc
	v_sqrt_f32_e32 v15, v13
	s_nop 0
	v_add_u32_e32 v71, -1, v15
	v_fma_f32 v73, -v71, v15, v13
	v_add_u32_e32 v72, 1, v15
	v_cmp_ge_f32_e64 s[4:5], 0, v73
	s_nop 1
	v_cndmask_b32_e64 v71, v15, v71, s[4:5]
	v_fma_f32 v15, -v72, v15, v13
	v_cmp_lt_f32_e64 s[4:5], 0, v15
	s_nop 1
	v_cndmask_b32_e64 v15, v71, v72, s[4:5]
	v_mul_f32_e32 v71, 0x37800000, v15
	v_cndmask_b32_e32 v15, v15, v71, vcc
	v_cmp_class_f32_e32 vcc, v13, v216
	s_nop 1
	v_cndmask_b32_e32 v13, v15, v13, vcc
	v_div_scale_f32 v15, s[4:5], v13, v13, 1.0
	v_rcp_f32_e32 v71, v15
	s_nop 0
	v_fma_f32 v72, -v15, v71, 1.0
	v_fmac_f32_e32 v71, v72, v71
	v_div_scale_f32 v72, vcc, 1.0, v13, 1.0
	v_mul_f32_e32 v73, v72, v71
	v_fma_f32 v74, -v15, v73, v72
	v_fmac_f32_e32 v73, v74, v71
	v_fma_f32 v15, -v15, v73, v72
	v_div_fmas_f32 v15, v15, v71, v73
	v_div_fixup_f32 v72, v15, v13, 1.0
	v_pk_mul_f32 v[18:19], v[72:73], v[18:19] op_sel_hi:[0,1]
	s_waitcnt vmcnt(13)
	v_pk_mul_f32 v[18:19], v[18:19], v[46:47]
	v_pk_mul_f32 v[16:17], v[72:73], v[16:17] op_sel_hi:[0,1]
	v_pk_mul_f32 v[46:47], v[18:19], v[48:49] op_sel:[1,0] op_sel_hi:[0,1]
	v_pk_mul_f32 v[18:19], v[18:19], v[48:49]
	s_waitcnt vmcnt(11)
	v_pk_mul_f32 v[48:49], v[16:17], v[50:51]
	v_pk_mul_f32 v[16:17], v[72:73], v[26:27] op_sel_hi:[0,1]
	v_pk_mul_f32 v[2:3], v[72:73], v[2:3] op_sel_hi:[0,1]
	v_pk_mul_f32 v[16:17], v[16:17], v[24:25]
	v_pk_mul_f32 v[2:3], v[2:3], v[34:35]
	v_pk_mul_f32 v[24:25], v[16:17], v[32:33] op_sel:[1,0] op_sel_hi:[0,1]
	v_pk_mul_f32 v[26:27], v[2:3], v[28:29] op_sel:[1,0] op_sel_hi:[0,1]
	v_pk_mul_f32 v[6:7], v[72:73], v[6:7] op_sel_hi:[0,1]
	v_pk_mul_f32 v[4:5], v[72:73], v[4:5] op_sel_hi:[0,1]
	v_pk_mul_f32 v[16:17], v[16:17], v[32:33]
	v_mov_b32_e32 v32, v24
	v_mov_b32_e32 v33, v26
	v_mov_b32_e32 v26, v25
	v_pk_mul_f32 v[2:3], v[2:3], v[28:29]
	v_pk_mul_f32 v[6:7], v[6:7], v[40:41]
	v_pk_mul_f32 v[4:5], v[4:5], v[44:45]
	v_pk_add_f32 v[24:25], v[32:33], v[26:27] neg_lo:[0,1] neg_hi:[0,1]
	v_mov_b32_e32 v26, v16
	v_mov_b32_e32 v27, v2
	v_mov_b32_e32 v2, v17
	v_pk_mul_f32 v[40:41], v[6:7], v[42:43] op_sel:[1,0] op_sel_hi:[0,1]
	v_pk_add_f32 v[16:17], v[26:27], v[2:3]
	v_cvt_pk_bf16_f32 v2, v24, v25
	v_pk_mul_f32 v[24:25], v[4:5], v[30:31] op_sel:[1,0] op_sel_hi:[0,1]
	v_pk_mul_f32 v[6:7], v[6:7], v[42:43]
	v_mov_b32_e32 v26, v40
	v_mov_b32_e32 v27, v24
	v_mov_b32_e32 v24, v41
	v_pk_mul_f32 v[4:5], v[4:5], v[30:31]
	v_pk_add_f32 v[24:25], v[26:27], v[24:25] neg_lo:[0,1] neg_hi:[0,1]
	v_mov_b32_e32 v26, v6
	v_mov_b32_e32 v27, v4
	v_mov_b32_e32 v4, v7
	v_pk_add_f32 v[4:5], v[26:27], v[4:5]
	v_cvt_pk_bf16_f32 v16, v16, v17
	v_cvt_pk_bf16_f32 v17, v4, v5
	v_pk_mul_f32 v[4:5], v[48:49], v[36:37] op_sel:[1,0] op_sel_hi:[0,1]
	v_mov_b32_e32 v6, v46
	v_mov_b32_e32 v7, v4
	v_mov_b32_e32 v4, v47
	v_pk_add_f32 v[4:5], v[6:7], v[4:5] neg_lo:[0,1] neg_hi:[0,1]
	v_pk_mul_f32 v[6:7], v[48:49], v[36:37]
	v_pk_mul_f32 v[22:23], v[72:73], v[22:23] op_sel_hi:[0,1]
	v_pk_mul_f32 v[20:21], v[72:73], v[20:21] op_sel_hi:[0,1]
	v_cvt_pk_bf16_f32 v3, v24, v25
	v_mov_b32_e32 v24, v18
	v_mov_b32_e32 v25, v6
	v_mov_b32_e32 v6, v19
	s_waitcnt vmcnt(9)
	v_pk_mul_f32 v[22:23], v[22:23], v[52:53]
	s_waitcnt vmcnt(7)
	v_pk_mul_f32 v[20:21], v[20:21], v[56:57]
	v_pk_add_f32 v[6:7], v[24:25], v[6:7]
	v_pk_mul_f32 v[52:53], v[22:23], v[54:55] op_sel:[1,0] op_sel_hi:[0,1]
	v_cvt_pk_bf16_f32 v18, v6, v7
	v_pk_mul_f32 v[6:7], v[20:21], v[38:39] op_sel:[1,0] op_sel_hi:[0,1]
	v_pk_mul_f32 v[22:23], v[22:23], v[54:55]
	v_mov_b32_e32 v24, v52
	v_mov_b32_e32 v25, v6
	v_mov_b32_e32 v6, v53
	v_pk_mul_f32 v[20:21], v[20:21], v[38:39]
	v_pk_add_f32 v[6:7], v[24:25], v[6:7] neg_lo:[0,1] neg_hi:[0,1]
	v_mov_b32_e32 v24, v22
	v_mov_b32_e32 v25, v20
	v_mov_b32_e32 v20, v23
	v_pk_add_f32 v[20:21], v[24:25], v[20:21]
	v_cvt_pk_bf16_f32 v4, v4, v5
	v_cvt_pk_bf16_f32 v5, v6, v7
	v_cvt_pk_bf16_f32 v19, v20, v21
	global_store_dwordx4 v[0:1], v[2:5], off sc1
	global_store_dwordx4 v[0:1], v[16:19], off offset:64 sc1
	s_cbranch_scc1 .LBB0_1012
.LBB0_992:
	s_waitcnt vmcnt(2)
	s_ashr_i32 s3, s2, 31
	s_lshl_b64 s[4:5], s[2:3], 13
	s_mul_hi_i32 s3, s2, 0x38e38e39
	s_lshr_b32 s8, s3, 31
	s_ashr_i32 s3, s3, 9
	s_add_i32 s3, s3, s8
	s_mulk_i32 s3, 0x900
	s_sub_i32 s3, s2, s3
	s_cmpk_gt_i32 s3, 0xff
	s_cselect_b64 s[8:9], -1, 0
	s_add_i32 s10, s3, 0xffffff00
	s_ashr_i32 s10, s10, 6
	v_cvt_f32_i32_e32 v24, s10
	s_and_b32 s10, s3, 63
	s_cmpk_lt_i32 s3, 0x100
	v_cvt_f32_ubyte0_e32 v25, s10
	s_cbranch_scc1 .LBB0_996
	v_lshl_add_u64 v[16:17], v[10:11], 0, s[4:5]
	s_mov_b64 s[10:11], 0
	v_mov_b32_e32 v13, v70
	v_mov_b32_e32 v15, v58
.LBB0_994:
	v_and_b32_e32 v0, 2, v15
	v_cmp_eq_u32_e32 vcc, 0, v0
	s_cmp_lg_u64 s[10:11], 0
	s_cbranch_scc1 .Lp3_pass2
	v_mov_b32_e32 v4, v126
	v_mov_b32_e32 v5, v127
	v_mov_b32_e32 v6, v128
	v_mov_b32_e32 v7, v129
	v_mov_b32_e32 v0, v130
	v_mov_b32_e32 v1, v131
	v_mov_b32_e32 v2, v132
	v_mov_b32_e32 v3, v133
	s_branch .Lp3_loaded

.Lp3_loaded:
	v_and_b32_e32 v23, 8, v13
	v_cvt_f32_ubyte0_e32 v18, v23
	v_mul_f32_e32 v18, 0xbf549a78, v18
	v_exp_f32_e32 v18, v18
	v_cndmask_b32_e32 v22, v25, v24, vcc
	s_mov_b64 s[12:13], 0x800
	v_cmp_lt_u32_e32 vcc, 31, v15
	v_mul_f32_e32 v18, 0.15915494, v18
	v_mul_f32_e32 v19, v22, v18
	v_floor_f32_e32 v19, v19
	v_fma_f32 v19, v22, v18, -v19
	v_sin_f32_e32 v18, v19
	v_cos_f32_e32 v20, v19
	v_or_b32_e32 v19, 1, v23
	v_cvt_f32_ubyte0_e32 v19, v19
	v_mul_f32_e32 v19, 0xbf549a78, v19
	v_exp_f32_e32 v19, v19
	v_add_u32_e32 v13, 0x200, v13
	s_or_b64 s[10:11], vcc, s[10:11]
	v_mul_f32_e32 v19, 0.15915494, v19
	v_mul_f32_e32 v21, v22, v19
	v_floor_f32_e32 v21, v21
	v_fma_f32 v21, v22, v19, -v21
	v_sin_f32_e32 v19, v21
	v_cos_f32_e32 v21, v21
	v_lshlrev_b32_e32 v26, 16, v4
	v_lshlrev_b32_e32 v28, 16, v0
	v_and_b32_e32 v29, 0xffff0000, v0
	v_and_b32_e32 v27, 0xffff0000, v4
	v_pk_mul_f32 v[30:31], v[20:21], v[28:29]
	s_nop 0
	v_pk_fma_f32 v[30:31], v[18:19], v[26:27], v[30:31]
	v_pk_mul_f32 v[18:19], v[18:19], v[28:29]
	v_lshlrev_b32_e32 v28, 16, v1
	v_pk_fma_f32 v[18:19], v[20:21], v[26:27], v[18:19] neg_lo:[0,0,1] neg_hi:[0,0,1]
	v_and_b32_e32 v29, 0xffff0000, v1
	v_cvt_pk_bf16_f32 v4, v18, v19
	v_or_b32_e32 v18, 2, v23
	v_cvt_f32_ubyte0_e32 v18, v18
	v_mul_f32_e32 v18, 0xbf549a78, v18
	v_exp_f32_e32 v18, v18
	v_cvt_pk_bf16_f32 v0, v30, v31
	v_lshlrev_b32_e32 v26, 16, v5
	v_and_b32_e32 v27, 0xffff0000, v5
	v_mul_f32_e32 v18, 0.15915494, v18
	v_mul_f32_e32 v19, v22, v18
	v_floor_f32_e32 v19, v19
	v_fma_f32 v19, v22, v18, -v19
	v_sin_f32_e32 v18, v19
	v_cos_f32_e32 v20, v19
	v_or_b32_e32 v19, 3, v23
	v_cvt_f32_ubyte0_e32 v19, v19
	v_mul_f32_e32 v19, 0xbf549a78, v19
	v_exp_f32_e32 v19, v19
	s_nop 0
	v_mul_f32_e32 v19, 0.15915494, v19
	v_mul_f32_e32 v21, v22, v19
	v_floor_f32_e32 v21, v21
	v_fma_f32 v21, v22, v19, -v21
	v_sin_f32_e32 v19, v21
	v_cos_f32_e32 v21, v21
	s_nop 0
	v_pk_mul_f32 v[30:31], v[20:21], v[28:29]
	s_nop 0
	v_pk_fma_f32 v[30:31], v[18:19], v[26:27], v[30:31]
	v_pk_mul_f32 v[18:19], v[18:19], v[28:29]
	v_lshlrev_b32_e32 v28, 16, v2
	v_pk_fma_f32 v[18:19], v[20:21], v[26:27], v[18:19] neg_lo:[0,0,1] neg_hi:[0,0,1]
	v_and_b32_e32 v29, 0xffff0000, v2
	v_cvt_pk_bf16_f32 v5, v18, v19
	v_or_b32_e32 v18, 4, v23
	v_cvt_f32_ubyte0_e32 v18, v18
	v_mul_f32_e32 v18, 0xbf549a78, v18
	v_exp_f32_e32 v18, v18
	v_cvt_pk_bf16_f32 v1, v30, v31
	v_lshlrev_b32_e32 v26, 16, v6
	v_and_b32_e32 v27, 0xffff0000, v6
	v_mul_f32_e32 v18, 0.15915494, v18
	v_mul_f32_e32 v19, v22, v18
	v_floor_f32_e32 v19, v19
	v_fma_f32 v19, v22, v18, -v19
	v_sin_f32_e32 v18, v19
	v_cos_f32_e32 v20, v19
	v_or_b32_e32 v19, 5, v23
	v_cvt_f32_ubyte0_e32 v19, v19
	v_mul_f32_e32 v19, 0xbf549a78, v19
	v_exp_f32_e32 v19, v19
	s_nop 0
	v_mul_f32_e32 v19, 0.15915494, v19
	v_mul_f32_e32 v21, v22, v19
	v_floor_f32_e32 v21, v21
	v_fma_f32 v21, v22, v19, -v21
	v_sin_f32_e32 v19, v21
	v_cos_f32_e32 v21, v21
	s_nop 0
	v_pk_mul_f32 v[30:31], v[20:21], v[28:29]
	s_nop 0
	v_pk_fma_f32 v[30:31], v[18:19], v[26:27], v[30:31]
	v_pk_mul_f32 v[18:19], v[18:19], v[28:29]
	v_cvt_pk_bf16_f32 v2, v30, v31
	v_pk_fma_f32 v[18:19], v[20:21], v[26:27], v[18:19] neg_lo:[0,0,1] neg_hi:[0,0,1]
	v_lshlrev_b32_e32 v26, 16, v3
	v_cvt_pk_bf16_f32 v6, v18, v19
	v_or_b32_e32 v18, 6, v23
	v_cvt_f32_ubyte0_e32 v18, v18
	v_mul_f32_e32 v18, 0xbf549a78, v18
	v_exp_f32_e32 v18, v18
	v_and_b32_e32 v27, 0xffff0000, v3
	v_mul_f32_e32 v18, 0.15915494, v18
	v_mul_f32_e32 v19, v22, v18
	v_floor_f32_e32 v19, v19
	v_fma_f32 v19, v22, v18, -v19
	v_sin_f32_e32 v18, v19
	v_cos_f32_e32 v20, v19
	v_or_b32_e32 v19, 7, v23
	v_cvt_f32_ubyte0_e32 v19, v19
	v_mul_f32_e32 v19, 0xbf549a78, v19
	v_exp_f32_e32 v19, v19
	v_and_b32_e32 v23, 0xffff0000, v7
	v_mul_f32_e32 v19, 0.15915494, v19
	v_mul_f32_e32 v21, v22, v19
	v_floor_f32_e32 v21, v21
	v_fma_f32 v21, v22, v19, -v21
	v_sin_f32_e32 v19, v21
	v_cos_f32_e32 v21, v21
	v_lshlrev_b32_e32 v22, 16, v7
	v_pk_mul_f32 v[28:29], v[20:21], v[26:27]
	s_nop 0
	v_pk_fma_f32 v[28:29], v[18:19], v[22:23], v[28:29]
	v_pk_mul_f32 v[18:19], v[18:19], v[26:27]
	v_cvt_pk_bf16_f32 v3, v28, v29
	v_pk_fma_f32 v[18:19], v[20:21], v[22:23], v[18:19] neg_lo:[0,0,1] neg_hi:[0,0,1]
	s_nop 0
	v_cvt_pk_bf16_f32 v7, v18, v19
	global_store_dwordx4 v[16:17], v[4:7], off sc1
	global_store_dwordx4 v[16:17], v[0:3], off offset:32 sc1
	v_lshl_add_u64 v[16:17], v[16:17], 0, s[12:13]
	s_nop 0
	v_add_u32_e32 v0, 64, v15
	v_mov_b32_e32 v15, v0
	s_andn2_b64 exec, exec, s[10:11]
	s_cbranch_execnz .LBB0_994
	s_or_b64 exec, exec, s[10:11]
.LBB0_996:
	v_readlane_b32 s10, v253, 56
	v_readlane_b32 s11, v253, 57
	s_add_u32 s4, s10, s4
	s_addc_u32 s5, s11, s5
	v_lshl_add_u64 v[0:1], s[4:5], 0, v[176:177]
	v_mov_b32_e32 v13, v177
	v_lshl_add_u64 v[0:1], v[0:1], 0, v[12:13]
	v_mov_b32_e32 v15, v177
	v_lshl_add_u64 v[2:3], v[0:1], 0, v[14:15]
	s_mov_b64 s[4:5], 0x1600
	v_lshl_add_u64 v[0:1], v[2:3], 0, s[4:5]
	v_add_co_u32_e32 v2, vcc, 0x1000, v2
	v_cndmask_b32_e64 v13, v25, v24, s[6:7]
	s_nop 0
	v_addc_co_u32_e32 v3, vcc, 0, v3, vcc
	s_andn2_b64 vcc, exec, s[8:9]
	v_mov_b32_e32 v26, v100
	v_mov_b32_e32 v27, v101
	v_mov_b32_e32 v28, v102
	v_mov_b32_e32 v29, v103
	v_mov_b32_e32 v30, v104
	v_mov_b32_e32 v31, v105
	v_mov_b32_e32 v32, v106
	v_mov_b32_e32 v33, v107
	v_mov_b32_e32 v25, v124
	v_and_b32_e32 v3, 0xffff0000, v26
	v_and_b32_e32 v2, 0xffff0000, v30
	v_lshlrev_b32_e32 v7, 16, v27
	v_and_b32_e32 v5, 0xffff0000, v27
	v_lshlrev_b32_e32 v27, 16, v26
	v_lshlrev_b32_e32 v26, 16, v30
	v_lshlrev_b32_e32 v6, 16, v31
	v_and_b32_e32 v4, 0xffff0000, v31
	v_lshlrev_b32_e32 v19, 16, v28
	v_and_b32_e32 v17, 0xffff0000, v28
	v_lshlrev_b32_e32 v23, 16, v29
	v_and_b32_e32 v21, 0xffff0000, v29
	v_pk_mul_f32 v[28:29], v[2:3], v[2:3]
	v_pk_mul_f32 v[30:31], v[26:27], v[26:27]
	v_lshlrev_b32_e32 v18, 16, v32
	v_and_b32_e32 v16, 0xffff0000, v32
	v_lshlrev_b32_e32 v22, 16, v33
	v_and_b32_e32 v20, 0xffff0000, v33
	v_pk_mul_f32 v[32:33], v[6:7], v[6:7]
	v_add_f32_e32 v24, v29, v28
	v_add_f32_e32 v28, v31, v30
	v_pk_mul_f32 v[34:35], v[4:5], v[4:5]
	v_mov_b32_e32 v38, v18
	v_mov_b32_e32 v39, v16
	v_add_f32_e32 v24, v28, v24
	v_add_f32_e32 v28, v33, v32
	v_mov_b32_e32 v36, v19
	v_mov_b32_e32 v37, v17
	v_pk_mul_f32 v[38:39], v[38:39], v[38:39]
	v_add_f32_e32 v15, v35, v34
	v_add_f32_e32 v24, v24, v28
	v_pk_fma_f32 v[36:37], v[36:37], v[36:37], v[38:39]
	v_mov_b32_e32 v40, v22
	v_mov_b32_e32 v41, v20
	v_add_f32_e32 v15, v24, v15
	v_mov_b32_e32 v38, v23
	v_mov_b32_e32 v39, v21
	v_pk_mul_f32 v[40:41], v[40:41], v[40:41]
	v_add_f32_e32 v15, v15, v36
	v_pk_fma_f32 v[38:39], v[38:39], v[38:39], v[40:41]
	v_add_f32_e32 v15, v15, v37
	v_add_f32_e32 v15, v15, v38
	v_add_f32_e32 v15, v15, v39
	ds_bpermute_b32 v24, v59, v15
	v_cndmask_b32_e64 v30, 0, 1, s[8:9]
	v_mov_b32_e32 v29, 0
	v_mov_b32_e32 v28, 1.0
	v_cmp_ne_u32_e64 s[4:5], 1, v30
	s_waitcnt lgkmcnt(0)
	v_add_f32_e32 v15, v15, v24
	ds_bpermute_b32 v24, v60, v15
	v_mov_b32_e32 v32, 1.0
	v_mov_b32_e32 v33, 0
	s_waitcnt lgkmcnt(0)
	v_add_f32_e32 v15, v15, v24
	global_load_dword v24, v[8:9], off offset:128
	ds_bpermute_b32 v71, v61, v15
	s_cbranch_vccnz .LBB0_998
	v_mul_f32_e32 v30, v13, v62
	v_floor_f32_e32 v30, v30
	v_fma_f32 v30, v13, v62, -v30
	v_sin_f32_e32 v33, v30
	v_cos_f32_e32 v32, v30
